# strategy 7.4 other half: static s_setprio 1 for waves 0-3 during the GEMM phases, per-segment flips deleted
# speedup vs baseline: 1.0087x; 1.0087x over previous
;     __device__ __forceinline__ bool next(int i, Unit& u) const { if (i != 0) return false; return base.next(which, u); }
;     __device__ __forceinline__ bool next(int i, Unit& u) const { if (i >= nrd) return false; u.pm = (rd0 + i) * 16 + 4 * xl + (j >> 3); u.pn = j & 7; return true; }
; template <class Epi, class Sched, bool ALIGN_EPI = false, bool SP2 = false>
; __device__ __forceinline__ void gemm_phase(PG8_LAS unsigned char* lds, const Gemm g, const Sched& S, const Epi& E, const int wave_id) {
;     ...
;     Unit cur, nxt; int ui = 0;
;     if (!S.next(0, cur)) return;
; template <int UPTO>
; __device__ __forceinline__ void program(Frame& F, const XcdBarrier& bar, const XcdBarrier& gbar, const XcdBarrier& sbar, const int half, const int xl, const int jx) {
;     ...
;         pg8::Gemm g{(const pg8::bf16_t*)(ws + WS_XB) + rb * DM, (const pg8::bf16_t*)(ws + WS_WIN), MH, NPROJ, DM}; pg8::StaticOrder S; S.init(MH, NPROJ, F.G, F.ch);
;         pg8::EpiProj E{(pg8::bf16_t*)(ws + WS_PROJ) + rb * NPROJ, (const float*)(ws + WS_RSTD) + rb, NPROJ, (pg8::bf16_t*)(ws + WS_UGM), (int)rb};
;         pg8::gemm_phase<pg8::EpiProj, pg8::StaticOrder, true, true>(F.lds + RING_OFF, g, S, E, F.wave);
.LBB0_153:
	s_and_b32 s55, s83, 3
	s_lshl_b32 s0, s86, 2
	s_or_b32 s69, s0, s55
	s_cmpk_lt_i32 s69, 0x200
	s_cselect_b64 s[0:1], -1, 0
	s_cmpk_gt_i32 s69, 0x1ff
	s_waitcnt lgkmcnt(0)
	s_barrier
	v_readlane_b32 s99, v254, 4
	s_cmp_lt_u32 s99, 0x100
	s_cbranch_scc0 .Lprio_done1
	s_setprio 1

; #define PG8_STAGE(bufoff, gbase, voff) do { _Pragma("unroll") for (int _i = 0; _i < 2; ++_i) \
;         __builtin_amdgcn_global_load_lds((const unsigned*)((const char*)(gbase) + (voff)[_i]), (PG8_LAS unsigned*)(lds + (bufoff) + ldsw + _i * 8192), 16, 0, 0); } while (0)
; #define PG8_WAIT_V(n) asm volatile("s_waitcnt vmcnt(" #n ")" ::: "memory")
; #define PG8_BAR __builtin_amdgcn_s_barrier()
; template <class Epi, class Sched, bool ALIGN_EPI = false, bool SP2 = false>
; __device__ __forceinline__ void gemm_phase(PG8_LAS unsigned char* lds, const Gemm g, const Sched& S, const Epi& E, const int wave_id) {
;     ...
;     if constexpr (SP2) {
;         PG8_STAGE(PG8_SB(0, 0), cB, voffB); PG8_STAGE(PG8_SB(0, 1), cB + hstep, voffB); PG8_STAGE(PG8_SA(0, 0), cA, voffA); PG8_STAGE(PG8_SA(0, 1), cA + hstep, voffA);
;         if (wr == 1) PG8_BAR;
;         PG8_WAIT_V(2); PG8_BAR;
;         PG8_STAGE(PG8_SB(1, 0), cB + kstep, voffB); PG8_STAGE(PG8_SA(1, 0), cA + kstep, voffA); PG8_STAGE(PG8_SB(1, 1), cB + hstep + kstep, voffB);
;         PG8_WAIT_V(6); PG8_BAR;
.LBB0_444:
	s_barrier
	v_readlane_b32 s99, v254, 4
	s_cmp_lt_u32 s99, 0x100
	s_cbranch_scc0 .Lprio_done2
	s_setprio 1
